# layer-0 weight-copy split: 1280 tiles in the prologue, 14 per idle workgroup in G1(0)'s tail (was 1536 / 13); on top of tail pulls 3/2
# speedup vs baseline: 1.0057x; 1.0057x over previous
.LBB0_84:
	s_or_b64 exec, exec, s[2:3]
	s_add_i32 s46, 0, 0x20180
	v_mov_b32_e32 v1, s46
	s_waitcnt lgkmcnt(0)
	s_barrier
	ds_read_b32 v1, v1
	s_mov_b32 s21, 0
	s_waitcnt lgkmcnt(0)
	v_readfirstlane_b32 s47, v1
	s_cmpk_gt_i32 s47, 0x4ff
	s_cbranch_scc1 .LBB0_147
	s_ashr_i32 s2, s22, 6
	v_bfe_u32 v3, v2, 5, 1
	v_and_b32_e32 v4, 31, v2
	v_lshlrev_b32_e32 v1, 1, v3
	s_lshl_b32 s3, s2, 3
	v_lshlrev_b32_e32 v3, 2, v3
	v_lshlrev_b32_e32 v54, 2, v4
	v_lshlrev_b32_e32 v55, 10, v4
	v_lshlrev_b32_e32 v4, 3, v4
	v_or_b32_e32 v5, s3, v3
	v_bitop3_b32 v57, s3, v4, v3 bitop3:0x36
	v_add_u32_e32 v3, 64, v5
	v_xor_b32_e32 v58, v3, v4
	v_add_u32_e32 v3, 0x80, v5
	v_xor_b32_e32 v59, v3, v4
	v_add_u32_e32 v3, 0xc0, v5
	v_lshl_or_b32 v1, s2, 2, v1
	s_lshl_b32 s4, s2, 4
	v_lshlrev_b32_e32 v7, 4, v2
	v_xor_b32_e32 v60, v3, v4
	s_lshl_b32 s2, s2, 5
	v_mov_b32_e32 v3, 0xf0
	v_bfe_u32 v6, v2, 4, 2
	v_bitop3_b32 v62, s2, v3, v7 bitop3:0x48
	s_or_b32 s2, s4, 8
	v_or_b32_e32 v4, s2, v6
	s_lshl_b32 s2, s2, 1
	v_bitop3_b32 v64, s2, v3, v7 bitop3:0x48
	s_or_b32 s2, s4, 12
	v_readlane_b32 s80, v250, 5
	v_lshlrev_b32_e32 v63, 8, v4
	v_or_b32_e32 v4, s2, v6
	s_lshl_b32 s2, s2, 1
	v_readlane_b32 s94, v250, 19
	v_readlane_b32 s95, v250, 20
	s_add_u32 s22, s94, 0x14400000
	s_addc_u32 s23, s95, 0
	s_add_u32 s24, s94, 0x9400000
	v_lshlrev_b32_e32 v2, 3, v2
	s_addc_u32 s25, s95, 0
	v_or_b32_e32 v56, s4, v6
	v_and_b32_e32 v2, 0x78, v2
	s_add_u32 s26, s94, 0x7400000
	v_mov_b32_e32 v51, 0
	v_lshlrev_b32_e32 v61, 8, v56
	v_lshlrev_b32_e32 v65, 8, v4
	v_bitop3_b32 v66, s2, v3, v7 bitop3:0x48
	s_addc_u32 s27, s95, 0
	v_lshlrev_b32_e32 v50, 1, v2
	v_mov_b32_e32 v67, 0x80
	v_mov_b32_e32 v68, 10
	v_mov_b32_e32 v69, 5
	v_mov_b32_e32 v70, 7
	s_mov_b32 s48, 0
	v_readlane_b32 s81, v250, 6
	v_readlane_b32 s82, v250, 7
	v_readlane_b32 s83, v250, 8
	v_readlane_b32 s84, v250, 9
	v_readlane_b32 s85, v250, 10
	v_readlane_b32 s86, v250, 11
	v_readlane_b32 s87, v250, 12
	v_readlane_b32 s88, v250, 13
	v_readlane_b32 s89, v250, 14
	v_readlane_b32 s90, v250, 15
	v_readlane_b32 s91, v250, 16
	v_readlane_b32 s92, v250, 17
	v_readlane_b32 s93, v250, 18
	s_branch .LBB0_87
.LBB0_86:
	s_or_b64 exec, exec, s[2:3]
	s_waitcnt vmcnt(0)
	v_mov_b32_e32 v2, s46
	s_waitcnt lgkmcnt(0)
	s_barrier
	ds_read_b32 v2, v2
	s_waitcnt lgkmcnt(0)
	v_readfirstlane_b32 s47, v2
	s_cmpk_lt_i32 s47, 0x500
	s_cbranch_scc0 .LBB0_147

.LBB0_91:
	s_or_b64 exec, exec, s[2:3]
	s_sub_i32 s2, 0x500, s47
	s_min_i32 s49, s2, 4
	s_max_i32 s2, s49, 1
	v_mov_b32_e32 v2, 0
	s_mov_b32 s50, 1
	s_lshl_b32 s51, s2, 3
	s_lshl_b32 s52, s47, 7
	s_lshl_b32 s53, s47, 3
	s_mov_b64 s[30:31], 0
	s_mov_b32 s54, 0
	v_mov_b32_e32 v3, v2
	v_mov_b32_e32 v4, v2
	v_mov_b32_e32 v5, v2
	v_mov_b32_e32 v10, v2
	v_mov_b32_e32 v11, v2
	v_mov_b32_e32 v12, v2
	v_mov_b32_e32 v13, v2
	v_mov_b32_e32 v18, v2
	v_mov_b32_e32 v19, v2
	v_mov_b32_e32 v20, v2
	v_mov_b32_e32 v21, v2
	v_mov_b32_e32 v26, v2
	v_mov_b32_e32 v27, v2
	v_mov_b32_e32 v28, v2
	v_mov_b32_e32 v29, v2
	v_mov_b32_e32 v6, v2
	v_mov_b32_e32 v7, v2
	v_mov_b32_e32 v8, v2
	v_mov_b32_e32 v9, v2
	v_mov_b32_e32 v14, v2
	v_mov_b32_e32 v15, v2
	v_mov_b32_e32 v16, v2
	v_mov_b32_e32 v17, v2
	v_mov_b32_e32 v22, v2
	v_mov_b32_e32 v23, v2
	v_mov_b32_e32 v24, v2
	v_mov_b32_e32 v25, v2
	v_mov_b32_e32 v30, v2
	v_mov_b32_e32 v31, v2
	v_mov_b32_e32 v32, v2
	v_mov_b32_e32 v33, v2
	s_branch .LBB0_93

.LBB0_406:
	v_readlane_b32 s0, v255, 2
	s_cmp_eq_u32 s0, 3
	v_readlane_b32 s1, v255, 3
	s_cbranch_scc1 .LBB0_469
	v_readlane_b32 s0, v253, 48
	v_readlane_b32 s1, v253, 49
	s_andn2_b64 vcc, exec, s[0:1]
	s_cbranch_vccnz .LBB0_469
	v_readlane_b32 s0, v255, 2
	v_readlane_b32 s8, v250, 5
	v_readlane_b32 s1, v255, 3
	v_mov_b32_e32 v2, v0
	v_readlane_b32 s9, v250, 6
	v_readlane_b32 s10, v250, 7
	v_readlane_b32 s11, v250, 8
	v_readlane_b32 s14, v250, 11
	v_readlane_b32 s15, v250, 12
	v_readlane_b32 s16, v250, 13
	v_readlane_b32 s17, v250, 14
	v_readlane_b32 s18, v250, 15
	v_readlane_b32 s19, v250, 16
	s_add_i32 s0, s0, 1
	s_cmp_eq_u32 s0, 1
	s_cselect_b32 s0, 0, s0
	v_readlane_b32 s12, v250, 9
	v_readfirstlane_b32 s1, v2
	v_readlane_b32 s13, v250, 10
	s_mov_b64 s[10:11], s[14:15]
	s_mov_b64 s[4:5], s[18:19]
	s_mov_b64 s[2:3], s[62:63]
	s_mov_b64 s[8:9], s[16:17]
	v_cmp_eq_u32_e32 vcc, 0, v2
	v_readlane_b32 s20, v250, 17
	v_readlane_b32 s21, v250, 18
	v_readlane_b32 s22, v250, 19
	v_readlane_b32 s23, v250, 20
	s_waitcnt vmcnt(0)
	s_barrier
	s_and_saveexec_b64 s[12:13], vcc
	s_cbranch_execz .LBB0_412
	s_mov_b64 s[16:17], exec
	v_mbcnt_lo_u32_b32 v3, s16, 0
	v_mbcnt_hi_u32_b32 v3, s17, v3
	v_cmp_eq_u32_e32 vcc, 0, v3
	s_and_saveexec_b64 s[14:15], vcc
	s_cbranch_execz .LBB0_411
	s_lshl_b32 s28, s0, 6
	s_lshl_b64 s[18:19], s[28:29], 2
	v_readlane_b32 s20, v252, 11
	s_add_u32 s18, s20, s18
	v_readlane_b32 s20, v252, 12
	s_addc_u32 s19, s20, s19
	v_readlane_b32 s20, v255, 2
	s_cmp_eq_u32 s20, 0
	s_cselect_b32 s20, 0x80, 0
	s_add_u32 s18, s18, s20
	s_addc_u32 s19, s19, 0
	s_bcnt1_i32_b64 s16, s[16:17]
	v_readlane_b32 s20, v255, 2
	s_cmp_eq_u32 s20, 0
	s_cselect_b32 s20, 14, 3
	s_mul_i32 s16, s16, s20
	s_waitcnt lgkmcnt(1)
	v_mov_b32_e32 v4, s16
	global_atomic_add v4, v67, v4, s[18:19] sc0

.LBB0_412:
	s_or_b64 exec, exec, s[12:13]
	v_readlane_b32 s12, v254, 19
	s_waitcnt lgkmcnt(0)
	s_barrier
	v_mov_b32_e32 v3, s12
	ds_read_b32 v3, v3
	s_waitcnt lgkmcnt(0)
	v_readfirstlane_b32 s25, v3
	v_readlane_b32 s12, v255, 2
	s_cmp_eq_u32 s12, 0
	s_cselect_b32 s12, 0x500, 0
	s_add_i32 s25, s25, s12
	s_cmpk_gt_i32 s25, 0xc3f
	s_cbranch_scc1 .LBB0_468
	s_ashr_i32 s14, s1, 6
	s_mul_i32 s16, s0, 0x2c00000
	s_mul_hi_u32 s17, s0, 0x2c00000
	s_add_u32 s4, s4, s16
	s_addc_u32 s5, s5, s17
	s_mul_i32 s13, s0, 0x5800000
	s_mov_b32 s1, s29
	s_mul_hi_u32 s12, s0, 0x5800000
	s_add_u32 s8, s8, s13
	s_addc_u32 s9, s9, s12
	s_lshl_b64 s[12:13], s[0:1], 24
	s_add_u32 s10, s10, s12
	s_addc_u32 s11, s11, s13
	s_mul_i32 s12, s0, 0x3000000
	v_bfe_u32 v3, v2, 5, 1
	s_mul_hi_u32 s13, s0, 0x3000000
	s_add_u32 s12, s2, s12
	s_addc_u32 s13, s3, s13
	v_lshlrev_b32_e32 v5, 1, v3
	s_lshl_b32 s2, s14, 3
	v_lshlrev_b32_e32 v3, 2, v3
	v_and_b32_e32 v4, 31, v2
	v_or_b32_e32 v6, s2, v3
	v_bfe_u32 v7, v2, 4, 2
	v_lshlrev_b32_e32 v8, 4, v2
	v_lshlrev_b32_e32 v2, 3, v2
	v_lshl_or_b32 v52, s14, 2, v5
	v_lshlrev_b32_e32 v53, 2, v4
	v_lshlrev_b32_e32 v54, 10, v4
	v_lshlrev_b32_e32 v5, 3, v4
	v_and_b32_e32 v4, 0x78, v2
	v_add_u32_e32 v2, 64, v6
	s_lshl_b32 s3, s14, 4
	v_bitop3_b32 v56, s2, v5, v3 bitop3:0x36
	v_xor_b32_e32 v57, v2, v5
	v_add_u32_e32 v2, 0x80, v6
	s_lshl_b32 s2, s14, 5
	v_mov_b32_e32 v3, 0xf0
	v_xor_b32_e32 v58, v2, v5
	v_add_u32_e32 v2, 0xc0, v6
	v_bitop3_b32 v61, s2, v3, v8 bitop3:0x48
	s_or_b32 s2, s3, 8
	v_xor_b32_e32 v59, v2, v5
	v_or_b32_e32 v2, s2, v7
	s_lshl_b32 s2, s2, 1
	s_sub_i32 s18, 0xc40, s25
	v_bitop3_b32 v63, s2, v3, v8 bitop3:0x48
	s_or_b32 s2, s3, 12
	v_readlane_b32 s51, v255, 2
	s_cmp_eq_u32 s51, 0
	s_cselect_b32 s51, 14, 3
	s_min_i32 s51, s18, s51
	v_lshlrev_b32_e32 v62, 8, v2
	v_or_b32_e32 v2, s2, v7
	s_lshl_b32 s2, s2, 1
	s_mul_i32 s14, s0, 0x1600000
	s_max_i32 s22, s51, 1
	v_readlane_b32 s18, v252, 13
	s_mul_hi_u32 s15, s0, 0x1600000
	s_add_u32 s14, s18, s14
	v_readlane_b32 s18, v252, 14
	s_addc_u32 s15, s18, s15
	v_readlane_b32 s18, v252, 15
	s_add_u32 s16, s18, s16
	v_readlane_b32 s18, v252, 16
	v_or_b32_e32 v55, s3, v7
	v_bitop3_b32 v65, s2, v3, v8 bitop3:0x48
	s_mul_hi_u32 s2, s0, 0x1b00000
	s_mul_i32 s3, s0, 0x1b00000
	s_addc_u32 s17, s18, s17
	s_lshl_b64 s[0:1], s[0:1], 23
	v_readlane_b32 s18, v252, 17
	s_add_u32 s18, s18, s0
	v_readlane_b32 s0, v252, 18
	s_addc_u32 s19, s0, s1
	v_readlane_b32 s0, v252, 1
	v_lshlrev_b32_e32 v64, 8, v2
	s_add_u32 s20, s0, s3
	v_readlane_b32 s0, v252, 2
	v_mov_b32_e32 v2, 0
	s_mov_b32 s50, 1
	v_lshlrev_b32_e32 v60, 8, v55
	s_addc_u32 s21, s0, s2
	s_lshl_b32 s52, s22, 3
	s_lshl_b32 s53, s25, 7
	s_lshl_b32 s54, s25, 3
	s_mov_b64 s[22:23], 0
	s_mov_b32 s55, 0
	v_lshlrev_b32_e32 v66, 1, v4
	s_mov_b32 s56, 0
	v_mov_b32_e32 v3, v2
	v_mov_b32_e32 v4, v2
	v_mov_b32_e32 v5, v2
	v_mov_b32_e32 v10, v2
	v_mov_b32_e32 v11, v2
	v_mov_b32_e32 v12, v2
	v_mov_b32_e32 v13, v2
	v_mov_b32_e32 v18, v2
	v_mov_b32_e32 v19, v2
	v_mov_b32_e32 v20, v2
	v_mov_b32_e32 v21, v2
	v_mov_b32_e32 v26, v2
	v_mov_b32_e32 v27, v2
	v_mov_b32_e32 v28, v2
	v_mov_b32_e32 v29, v2
	v_mov_b32_e32 v6, v2
	v_mov_b32_e32 v7, v2
	v_mov_b32_e32 v8, v2
	v_mov_b32_e32 v9, v2
	v_mov_b32_e32 v14, v2
	v_mov_b32_e32 v15, v2
	v_mov_b32_e32 v16, v2
	v_mov_b32_e32 v17, v2
	v_mov_b32_e32 v22, v2
	v_mov_b32_e32 v23, v2
	v_mov_b32_e32 v24, v2
	v_mov_b32_e32 v25, v2
	v_mov_b32_e32 v30, v2
	v_mov_b32_e32 v31, v2
	v_mov_b32_e32 v32, v2
	v_mov_b32_e32 v33, v2
	s_branch .LBB0_415
